# M_OUT epilogue hand-pipelined: 8 row groups through a 4-slot register ring with counted waits, row sums reduced at the end (on top of the 4-phase K-loop)
# baseline (speedup 1.0000x reference)
.LBB0_990:
	s_and_b64 vcc, exec, s[18:19]
	s_cbranch_vccz .LBB0_1055
	s_lshl_b32 s18, s5, 8
	s_ashr_i32 s19, s18, 31
	v_ashrrev_i32_e32 v187, 31, v186
	s_waitcnt lgkmcnt(0)
	v_lshl_add_u64 v[248:249], s[18:19], 2, v[176:177]
	v_lshlrev_b64 v[218:219], 12, v[186:187]
	v_lshl_add_u64 v[248:249], v[248:249], 0, v[218:219]
	s_mov_b32 s24, 0x10000
	s_mov_b32 s25, 0
	s_mov_b32 s42, 0x50000
	s_mov_b32 s43, 0
	global_load_dwordx4 v[130:133], v[248:249], off
	global_load_dwordx4 v[134:137], v[248:249], off offset:16
	global_load_dwordx4 v[138:141], v[248:249], off offset:512
	global_load_dwordx4 v[142:145], v[248:249], off offset:528
	v_lshl_add_u64 v[248:249], v[248:249], 0, s[24:25]
	global_load_dwordx4 v[146:149], v[248:249], off
	global_load_dwordx4 v[150:153], v[248:249], off offset:16
	global_load_dwordx4 v[154:157], v[248:249], off offset:512
	global_load_dwordx4 v[158:161], v[248:249], off offset:528
	v_lshl_add_u64 v[248:249], v[248:249], 0, s[24:25]
	global_load_dwordx4 v[232:235], v[248:249], off
	global_load_dwordx4 v[236:239], v[248:249], off offset:16
	global_load_dwordx4 v[240:243], v[248:249], off offset:512
	global_load_dwordx4 v[244:247], v[248:249], off offset:528
	v_lshl_add_u64 v[248:249], v[248:249], 0, s[24:25]
	global_load_dwordx4 v[188:191], v[248:249], off
	global_load_dwordx4 v[192:195], v[248:249], off offset:16
	global_load_dwordx4 v[196:199], v[248:249], off offset:512
	global_load_dwordx4 v[214:217], v[248:249], off offset:528
	v_lshl_add_u64 v[248:249], v[248:249], 0, s[42:43]
	v_lshlrev_b64 v[218:219], 11, v[186:187]
	v_lshl_add_u64 v[250:251], s[48:49], 0, v[218:219]
	v_lshl_add_u64 v[250:251], s[18:19], 1, v[250:251]
	v_lshlrev_b32_e32 v218, 1, v162
	v_mov_b32_e32 v219, 0
	v_lshl_add_u64 v[250:251], v[250:251], 0, v[218:219]
	v_lshl_add_u64 v[228:229], v[186:187], 2, s[56:57]
	v_xor_b32_e32 v226, 16, v224
	v_xor_b32_e32 v227, 32, v224
	v_lshlrev_b32_e32 v226, 2, v226
	v_lshlrev_b32_e32 v227, 2, v227
	s_mov_b32 s44, 0x8000
	s_mov_b32 s45, 0
	s_mov_b32 s100, 0x28000
	s_mov_b32 s101, 0
	s_waitcnt vmcnt(12)
	v_pk_add_f32 v[130:131], v[130:131], v[126:127]
	v_pk_add_f32 v[132:133], v[132:133], v[128:129]
	v_pk_add_f32 v[134:135], v[134:135], v[122:123]
	v_pk_add_f32 v[136:137], v[136:137], v[124:125]
	v_pk_add_f32 v[138:139], v[138:139], v[118:119]
	v_pk_add_f32 v[140:141], v[140:141], v[120:121]
	v_pk_add_f32 v[142:143], v[142:143], v[114:115]
	v_pk_add_f32 v[144:145], v[144:145], v[116:117]
	v_pk_mul_f32 v[114:115], v[130:131], v[130:131]
	v_pk_fma_f32 v[114:115], v[132:133], v[132:133], v[114:115]
	v_pk_fma_f32 v[114:115], v[134:135], v[134:135], v[114:115]
	v_pk_fma_f32 v[114:115], v[136:137], v[136:137], v[114:115]
	v_pk_fma_f32 v[114:115], v[138:139], v[138:139], v[114:115]
	v_pk_fma_f32 v[114:115], v[140:141], v[140:141], v[114:115]
	v_pk_fma_f32 v[114:115], v[142:143], v[142:143], v[114:115]
	v_pk_fma_f32 v[114:115], v[144:145], v[144:145], v[114:115]
	v_cvt_pk_bf16_f32 v126, v130, v131
	v_cvt_pk_bf16_f32 v127, v132, v133
	v_cvt_pk_bf16_f32 v128, v134, v135
	v_cvt_pk_bf16_f32 v129, v136, v137
	v_cvt_pk_bf16_f32 v122, v138, v139
	v_cvt_pk_bf16_f32 v123, v140, v141
	v_cvt_pk_bf16_f32 v124, v142, v143
	v_cvt_pk_bf16_f32 v125, v144, v145
	v_add_f32_e32 v114, v114, v115
	global_store_dwordx4 v[250:251], v[126:129], off
	global_store_dwordx4 v[250:251], v[122:125], off offset:256
	v_lshl_add_u64 v[250:251], v[250:251], 0, s[44:45]
	global_load_dwordx4 v[130:133], v[248:249], off
	global_load_dwordx4 v[134:137], v[248:249], off offset:16
	global_load_dwordx4 v[138:141], v[248:249], off offset:512
	global_load_dwordx4 v[142:145], v[248:249], off offset:528
	v_lshl_add_u64 v[248:249], v[248:249], 0, s[24:25]
	s_waitcnt vmcnt(14)
	v_pk_add_f32 v[146:147], v[146:147], v[110:111]
	v_pk_add_f32 v[148:149], v[148:149], v[112:113]
	v_pk_add_f32 v[150:151], v[150:151], v[106:107]
	v_pk_add_f32 v[152:153], v[152:153], v[108:109]
	v_pk_add_f32 v[154:155], v[154:155], v[102:103]
	v_pk_add_f32 v[156:157], v[156:157], v[104:105]
	v_pk_add_f32 v[158:159], v[158:159], v[98:99]
	v_pk_add_f32 v[160:161], v[160:161], v[100:101]
	v_pk_mul_f32 v[98:99], v[146:147], v[146:147]
	v_pk_fma_f32 v[98:99], v[148:149], v[148:149], v[98:99]
	v_pk_fma_f32 v[98:99], v[150:151], v[150:151], v[98:99]
	v_pk_fma_f32 v[98:99], v[152:153], v[152:153], v[98:99]
	v_pk_fma_f32 v[98:99], v[154:155], v[154:155], v[98:99]
	v_pk_fma_f32 v[98:99], v[156:157], v[156:157], v[98:99]
	v_pk_fma_f32 v[98:99], v[158:159], v[158:159], v[98:99]
	v_pk_fma_f32 v[98:99], v[160:161], v[160:161], v[98:99]
	v_cvt_pk_bf16_f32 v110, v146, v147
	v_cvt_pk_bf16_f32 v111, v148, v149
	v_cvt_pk_bf16_f32 v112, v150, v151
	v_cvt_pk_bf16_f32 v113, v152, v153
	v_cvt_pk_bf16_f32 v106, v154, v155
	v_cvt_pk_bf16_f32 v107, v156, v157
	v_cvt_pk_bf16_f32 v108, v158, v159
	v_cvt_pk_bf16_f32 v109, v160, v161
	v_add_f32_e32 v98, v98, v99
	global_store_dwordx4 v[250:251], v[110:113], off
	global_store_dwordx4 v[250:251], v[106:109], off offset:256
	v_lshl_add_u64 v[250:251], v[250:251], 0, s[44:45]
	global_load_dwordx4 v[146:149], v[248:249], off
	global_load_dwordx4 v[150:153], v[248:249], off offset:16
	global_load_dwordx4 v[154:157], v[248:249], off offset:512
	global_load_dwordx4 v[158:161], v[248:249], off offset:528
	v_lshl_add_u64 v[248:249], v[248:249], 0, s[24:25]
	s_waitcnt vmcnt(16)
	v_pk_add_f32 v[232:233], v[232:233], v[94:95]
	v_pk_add_f32 v[234:235], v[234:235], v[96:97]
	v_pk_add_f32 v[236:237], v[236:237], v[90:91]
	v_pk_add_f32 v[238:239], v[238:239], v[92:93]
	v_pk_add_f32 v[240:241], v[240:241], v[86:87]
	v_pk_add_f32 v[242:243], v[242:243], v[88:89]
	v_pk_add_f32 v[244:245], v[244:245], v[82:83]
	v_pk_add_f32 v[246:247], v[246:247], v[84:85]
	v_pk_mul_f32 v[82:83], v[232:233], v[232:233]
	v_pk_fma_f32 v[82:83], v[234:235], v[234:235], v[82:83]
	v_pk_fma_f32 v[82:83], v[236:237], v[236:237], v[82:83]
	v_pk_fma_f32 v[82:83], v[238:239], v[238:239], v[82:83]
	v_pk_fma_f32 v[82:83], v[240:241], v[240:241], v[82:83]
	v_pk_fma_f32 v[82:83], v[242:243], v[242:243], v[82:83]
	v_pk_fma_f32 v[82:83], v[244:245], v[244:245], v[82:83]
	v_pk_fma_f32 v[82:83], v[246:247], v[246:247], v[82:83]
	v_cvt_pk_bf16_f32 v94, v232, v233
	v_cvt_pk_bf16_f32 v95, v234, v235
	v_cvt_pk_bf16_f32 v96, v236, v237
	v_cvt_pk_bf16_f32 v97, v238, v239
	v_cvt_pk_bf16_f32 v90, v240, v241
	v_cvt_pk_bf16_f32 v91, v242, v243
	v_cvt_pk_bf16_f32 v92, v244, v245
	v_cvt_pk_bf16_f32 v93, v246, v247
	v_add_f32_e32 v82, v82, v83
	global_store_dwordx4 v[250:251], v[94:97], off
	global_store_dwordx4 v[250:251], v[90:93], off offset:256
	v_lshl_add_u64 v[250:251], v[250:251], 0, s[44:45]
	global_load_dwordx4 v[232:235], v[248:249], off
	global_load_dwordx4 v[236:239], v[248:249], off offset:16
	global_load_dwordx4 v[240:243], v[248:249], off offset:512
	global_load_dwordx4 v[244:247], v[248:249], off offset:528
	v_lshl_add_u64 v[248:249], v[248:249], 0, s[24:25]
	s_waitcnt vmcnt(18)
	v_pk_add_f32 v[188:189], v[188:189], v[78:79]
	v_pk_add_f32 v[190:191], v[190:191], v[80:81]
	v_pk_add_f32 v[192:193], v[192:193], v[74:75]
	v_pk_add_f32 v[194:195], v[194:195], v[76:77]
	v_pk_add_f32 v[196:197], v[196:197], v[70:71]
	v_pk_add_f32 v[198:199], v[198:199], v[72:73]
	v_pk_add_f32 v[214:215], v[214:215], v[66:67]
	v_pk_add_f32 v[216:217], v[216:217], v[68:69]
	v_pk_mul_f32 v[66:67], v[188:189], v[188:189]
	v_pk_fma_f32 v[66:67], v[190:191], v[190:191], v[66:67]
	v_pk_fma_f32 v[66:67], v[192:193], v[192:193], v[66:67]
	v_pk_fma_f32 v[66:67], v[194:195], v[194:195], v[66:67]
	v_pk_fma_f32 v[66:67], v[196:197], v[196:197], v[66:67]
	v_pk_fma_f32 v[66:67], v[198:199], v[198:199], v[66:67]
	v_pk_fma_f32 v[66:67], v[214:215], v[214:215], v[66:67]
	v_pk_fma_f32 v[66:67], v[216:217], v[216:217], v[66:67]
	v_cvt_pk_bf16_f32 v78, v188, v189
	v_cvt_pk_bf16_f32 v79, v190, v191
	v_cvt_pk_bf16_f32 v80, v192, v193
	v_cvt_pk_bf16_f32 v81, v194, v195
	v_cvt_pk_bf16_f32 v74, v196, v197
	v_cvt_pk_bf16_f32 v75, v198, v199
	v_cvt_pk_bf16_f32 v76, v214, v215
	v_cvt_pk_bf16_f32 v77, v216, v217
	v_add_f32_e32 v66, v66, v67
	global_store_dwordx4 v[250:251], v[78:81], off
	global_store_dwordx4 v[250:251], v[74:77], off offset:256
	v_lshl_add_u64 v[250:251], v[250:251], 0, s[100:101]
	global_load_dwordx4 v[188:191], v[248:249], off
	global_load_dwordx4 v[192:195], v[248:249], off offset:16
	global_load_dwordx4 v[196:199], v[248:249], off offset:512
	global_load_dwordx4 v[214:217], v[248:249], off offset:528
	s_waitcnt vmcnt(18)
	v_pk_add_f32 v[130:131], v[130:131], v[62:63]
	v_pk_add_f32 v[132:133], v[132:133], v[64:65]
	v_pk_add_f32 v[134:135], v[134:135], v[58:59]
	v_pk_add_f32 v[136:137], v[136:137], v[60:61]
	v_pk_add_f32 v[138:139], v[138:139], v[54:55]
	v_pk_add_f32 v[140:141], v[140:141], v[56:57]
	v_pk_add_f32 v[142:143], v[142:143], v[50:51]
	v_pk_add_f32 v[144:145], v[144:145], v[52:53]
	v_pk_mul_f32 v[50:51], v[130:131], v[130:131]
	v_pk_fma_f32 v[50:51], v[132:133], v[132:133], v[50:51]
	v_pk_fma_f32 v[50:51], v[134:135], v[134:135], v[50:51]
	v_pk_fma_f32 v[50:51], v[136:137], v[136:137], v[50:51]
	v_pk_fma_f32 v[50:51], v[138:139], v[138:139], v[50:51]
	v_pk_fma_f32 v[50:51], v[140:141], v[140:141], v[50:51]
	v_pk_fma_f32 v[50:51], v[142:143], v[142:143], v[50:51]
	v_pk_fma_f32 v[50:51], v[144:145], v[144:145], v[50:51]
	v_cvt_pk_bf16_f32 v62, v130, v131
	v_cvt_pk_bf16_f32 v63, v132, v133
	v_cvt_pk_bf16_f32 v64, v134, v135
	v_cvt_pk_bf16_f32 v65, v136, v137
	v_cvt_pk_bf16_f32 v58, v138, v139
	v_cvt_pk_bf16_f32 v59, v140, v141
	v_cvt_pk_bf16_f32 v60, v142, v143
	v_cvt_pk_bf16_f32 v61, v144, v145
	v_add_f32_e32 v50, v50, v51
	global_store_dwordx4 v[250:251], v[62:65], off
	global_store_dwordx4 v[250:251], v[58:61], off offset:256
	v_lshl_add_u64 v[250:251], v[250:251], 0, s[44:45]
	s_waitcnt vmcnt(14)
	v_pk_add_f32 v[146:147], v[146:147], v[46:47]
	v_pk_add_f32 v[148:149], v[148:149], v[48:49]
	v_pk_add_f32 v[150:151], v[150:151], v[42:43]
	v_pk_add_f32 v[152:153], v[152:153], v[44:45]
	v_pk_add_f32 v[154:155], v[154:155], v[38:39]
	v_pk_add_f32 v[156:157], v[156:157], v[40:41]
	v_pk_add_f32 v[158:159], v[158:159], v[34:35]
	v_pk_add_f32 v[160:161], v[160:161], v[36:37]
	v_pk_mul_f32 v[34:35], v[146:147], v[146:147]
	v_pk_fma_f32 v[34:35], v[148:149], v[148:149], v[34:35]
	v_pk_fma_f32 v[34:35], v[150:151], v[150:151], v[34:35]
	v_pk_fma_f32 v[34:35], v[152:153], v[152:153], v[34:35]
	v_pk_fma_f32 v[34:35], v[154:155], v[154:155], v[34:35]
	v_pk_fma_f32 v[34:35], v[156:157], v[156:157], v[34:35]
	v_pk_fma_f32 v[34:35], v[158:159], v[158:159], v[34:35]
	v_pk_fma_f32 v[34:35], v[160:161], v[160:161], v[34:35]
	v_cvt_pk_bf16_f32 v46, v146, v147
	v_cvt_pk_bf16_f32 v47, v148, v149
	v_cvt_pk_bf16_f32 v48, v150, v151
	v_cvt_pk_bf16_f32 v49, v152, v153
	v_cvt_pk_bf16_f32 v42, v154, v155
	v_cvt_pk_bf16_f32 v43, v156, v157
	v_cvt_pk_bf16_f32 v44, v158, v159
	v_cvt_pk_bf16_f32 v45, v160, v161
	v_add_f32_e32 v34, v34, v35
	global_store_dwordx4 v[250:251], v[46:49], off
	global_store_dwordx4 v[250:251], v[42:45], off offset:256
	v_lshl_add_u64 v[250:251], v[250:251], 0, s[44:45]
	s_waitcnt vmcnt(10)
	v_pk_add_f32 v[232:233], v[232:233], v[30:31]
	v_pk_add_f32 v[234:235], v[234:235], v[32:33]
	v_pk_add_f32 v[236:237], v[236:237], v[26:27]
	v_pk_add_f32 v[238:239], v[238:239], v[28:29]
	v_pk_add_f32 v[240:241], v[240:241], v[22:23]
	v_pk_add_f32 v[242:243], v[242:243], v[24:25]
	v_pk_add_f32 v[244:245], v[244:245], v[18:19]
	v_pk_add_f32 v[246:247], v[246:247], v[20:21]
	v_pk_mul_f32 v[18:19], v[232:233], v[232:233]
	v_pk_fma_f32 v[18:19], v[234:235], v[234:235], v[18:19]
	v_pk_fma_f32 v[18:19], v[236:237], v[236:237], v[18:19]
	v_pk_fma_f32 v[18:19], v[238:239], v[238:239], v[18:19]
	v_pk_fma_f32 v[18:19], v[240:241], v[240:241], v[18:19]
	v_pk_fma_f32 v[18:19], v[242:243], v[242:243], v[18:19]
	v_pk_fma_f32 v[18:19], v[244:245], v[244:245], v[18:19]
	v_pk_fma_f32 v[18:19], v[246:247], v[246:247], v[18:19]
	v_cvt_pk_bf16_f32 v30, v232, v233
	v_cvt_pk_bf16_f32 v31, v234, v235
	v_cvt_pk_bf16_f32 v32, v236, v237
	v_cvt_pk_bf16_f32 v33, v238, v239
	v_cvt_pk_bf16_f32 v26, v240, v241
	v_cvt_pk_bf16_f32 v27, v242, v243
	v_cvt_pk_bf16_f32 v28, v244, v245
	v_cvt_pk_bf16_f32 v29, v246, v247
	v_add_f32_e32 v18, v18, v19
	global_store_dwordx4 v[250:251], v[30:33], off
	global_store_dwordx4 v[250:251], v[26:29], off offset:256
	v_lshl_add_u64 v[250:251], v[250:251], 0, s[44:45]
	s_waitcnt vmcnt(6)
	v_pk_add_f32 v[188:189], v[188:189], v[14:15]
	v_pk_add_f32 v[190:191], v[190:191], v[16:17]
	v_pk_add_f32 v[192:193], v[192:193], v[10:11]
	v_pk_add_f32 v[194:195], v[194:195], v[12:13]
	v_pk_add_f32 v[196:197], v[196:197], v[6:7]
	v_pk_add_f32 v[198:199], v[198:199], v[8:9]
	v_pk_add_f32 v[214:215], v[214:215], v[2:3]
	v_pk_add_f32 v[216:217], v[216:217], v[4:5]
	v_pk_mul_f32 v[2:3], v[188:189], v[188:189]
	v_pk_fma_f32 v[2:3], v[190:191], v[190:191], v[2:3]
	v_pk_fma_f32 v[2:3], v[192:193], v[192:193], v[2:3]
	v_pk_fma_f32 v[2:3], v[194:195], v[194:195], v[2:3]
	v_pk_fma_f32 v[2:3], v[196:197], v[196:197], v[2:3]
	v_pk_fma_f32 v[2:3], v[198:199], v[198:199], v[2:3]
	v_pk_fma_f32 v[2:3], v[214:215], v[214:215], v[2:3]
	v_pk_fma_f32 v[2:3], v[216:217], v[216:217], v[2:3]
	v_cvt_pk_bf16_f32 v14, v188, v189
	v_cvt_pk_bf16_f32 v15, v190, v191
	v_cvt_pk_bf16_f32 v16, v192, v193
	v_cvt_pk_bf16_f32 v17, v194, v195
	v_cvt_pk_bf16_f32 v10, v196, v197
	v_cvt_pk_bf16_f32 v11, v198, v199
	v_cvt_pk_bf16_f32 v12, v214, v215
	v_cvt_pk_bf16_f32 v13, v216, v217
	v_add_f32_e32 v2, v2, v3
	global_store_dwordx4 v[250:251], v[14:17], off
	global_store_dwordx4 v[250:251], v[10:13], off offset:256
	ds_bpermute_b32 v115, v226, v114
	ds_bpermute_b32 v99, v226, v98
	ds_bpermute_b32 v83, v226, v82
	ds_bpermute_b32 v67, v226, v66
	ds_bpermute_b32 v51, v226, v50
	ds_bpermute_b32 v35, v226, v34
	ds_bpermute_b32 v19, v226, v18
	ds_bpermute_b32 v3, v226, v2
	s_waitcnt lgkmcnt(0)
	v_add_f32_e32 v114, v114, v115
	v_add_f32_e32 v98, v98, v99
	v_add_f32_e32 v82, v82, v83
	v_add_f32_e32 v66, v66, v67
	v_add_f32_e32 v50, v50, v51
	v_add_f32_e32 v34, v34, v35
	v_add_f32_e32 v18, v18, v19
	v_add_f32_e32 v2, v2, v3
	ds_bpermute_b32 v115, v227, v114
	ds_bpermute_b32 v99, v227, v98
	ds_bpermute_b32 v83, v227, v82
	ds_bpermute_b32 v67, v227, v66
	ds_bpermute_b32 v51, v227, v50
	ds_bpermute_b32 v35, v227, v34
	ds_bpermute_b32 v19, v227, v18
	ds_bpermute_b32 v3, v227, v2
	s_waitcnt lgkmcnt(0)
	v_add_f32_e32 v114, v114, v115
	v_add_f32_e32 v98, v98, v99
	v_add_f32_e32 v82, v82, v83
	v_add_f32_e32 v66, v66, v67
	v_add_f32_e32 v50, v50, v51
	v_add_f32_e32 v34, v34, v35
	v_add_f32_e32 v18, v18, v19
	v_add_f32_e32 v2, v2, v3
	s_mov_b64 s[18:19], exec
	s_and_b64 exec, exec, s[40:41]
	global_atomic_add_f32 v[228:229], v114, off
	global_atomic_add_f32 v[228:229], v98, off offset:64
	global_atomic_add_f32 v[228:229], v82, off offset:128
	global_atomic_add_f32 v[228:229], v66, off offset:192
	global_atomic_add_f32 v[228:229], v50, off offset:512
	global_atomic_add_f32 v[228:229], v34, off offset:576
	global_atomic_add_f32 v[228:229], v18, off offset:640
	global_atomic_add_f32 v[228:229], v2, off offset:704
	s_mov_b64 exec, s[18:19]
